# P4: half of the workgroups (bx bit 3) run the sample K-slice unit before the full tile, staggering epilogue bursts
# baseline (speedup 1.0000x reference)
.LBB0_545:
	s_or_b64 exec, exec, s[4:5]
	s_cmpk_lg_i32 s26, 0x100
	s_cselect_b64 s[38:39], -1, 0
	s_cmpk_eq_i32 s26, 0x100
	s_waitcnt lgkmcnt(0)
	v_mov_b32_e32 v0, v164
	s_mov_b32 s4, 0
	s_cselect_b64 s[42:43], -1, 0
	s_barrier
	s_ashr_i32 s5, s4, 31
	s_lshl_b64 s[4:5], s[4:5], 3
	s_add_u32 s4, s0, s4
	s_mov_b32 s6, 1
	s_addc_u32 s5, s1, s5
	s_ashr_i32 s7, s6, 31
	s_lshl_b64 s[6:7], s[6:7], 3
	s_add_u32 s6, s0, s6
	v_mov_b32_e32 v8, v164
	s_mov_b32 s9, 0
	s_addc_u32 s7, s1, s7
	s_and_b64 vcc, exec, s[42:43]
	v_readfirstlane_b32 s46, v8
	s_mov_b32 s98, 0
	s_mov_b32 s99, 32
	s_mov_b32 s100, 0
	s_mov_b32 s101, 0
	s_cbranch_vccz .LBB0_573
	s_lshl_b32 s3, s2, 5
	s_and_b32 s3, s3, 0xe0
	s_ashr_i32 s8, s2, 3
	s_add_i32 s3, s3, s8
	s_ashr_i32 s14, s3, 3
	s_and_b32 s8, s8, 7
	s_bitcmp1_b32 s2, 3
	s_cbranch_scc0 .Lsw4_a
	s_lshl_b32 s98, s8, 9
	s_add_i32 s100, s8, 1
	s_and_b32 s8, s14, 7
	s_lshr_b32 s14, s14, 3
	s_add_i32 s14, s14, 32
	s_mov_b32 s99, 4
	s_mov_b32 s101, 32
.Lsw4_a:
	s_mov_b64 s[10:11], -1
	s_cbranch_execz .LBB0_574
	s_and_b64 vcc, exec, s[10:11]
	s_cbranch_vccz .LBB0_577
.LBB0_548:
	v_ashrrev_i32_e32 v1, 31, v8
	v_lshrrev_b32_e32 v1, 26, v1
	v_add_u32_e32 v1, v8, v1
	v_ashrrev_i32_e32 v9, 6, v1
	v_bfe_i32 v1, v8, 27, 1
	v_lshlrev_b32_e32 v0, 4, v8
	v_lshrrev_b32_e32 v1, 22, v1
	v_add_u32_e32 v1, v0, v1
	v_and_b32_e32 v1, 0xfffffc00, v1
	v_sub_u32_e32 v1, v0, v1
	v_lshrrev_b32_e32 v2, 4, v1
	v_bitop3_b32 v1, v2, v1, 32 bitop3:0x6c
	v_ashrrev_i32_e32 v3, 31, v1
	v_lshrrev_b32_e32 v3, 26, v3
	v_add_u32_e32 v3, v1, v3
	v_lshlrev_b32_e32 v2, 3, v9
	v_ashrrev_i32_e32 v10, 6, v3
	v_and_b32_e32 v3, 0xc0, v3
	v_and_b32_e32 v2, -16, v2
	v_sub_u32_e32 v1, v1, v3
	v_mov_b32_e32 v3, 1
	v_add_u32_e32 v2, v10, v2
	v_ashrrev_i16_sdwa v1, v3, sext(v1) dst_sel:DWORD dst_unused:UNUSED_PAD src0_sel:DWORD src1_sel:BYTE_0
	v_lshlrev_b32_e32 v4, 5, v9
	v_bfe_i32 v11, v1, 0, 16
	v_lshlrev_b32_e32 v1, 1, v2
	v_lshrrev_b32_e32 v5, 2, v2
	v_and_b32_e32 v6, 3, v10
	s_mov_b32 s10, 0xfffe0
	v_and_b32_e32 v4, 32, v4
	v_and_b32_e32 v1, 24, v1
	v_and_b32_e32 v5, 4, v5
	v_and_or_b32 v6, v2, s10, v6
	v_or3_b32 v1, v6, v5, v1
	v_add_lshl_u32 v4, v4, v11, 1
	v_add_u32_e32 v0, 0x2000, v0
	v_lshl_add_u32 v130, v1, 12, v4
	v_ashrrev_i32_e32 v1, 31, v0
	v_lshrrev_b32_e32 v1, 22, v1
	v_add_u32_e32 v1, v0, v1
	v_ashrrev_i32_e32 v12, 10, v1
	v_mul_i32_i24_e32 v1, 0x400, v12
	v_sub_u32_e32 v0, v0, v1
	v_lshrrev_b32_e32 v1, 4, v0
	v_bitop3_b32 v0, v1, v0, 32 bitop3:0x6c
	v_lshl_add_u32 v128, v2, 12, v4
	v_ashrrev_i32_e32 v2, 31, v0
	v_lshrrev_b32_e32 v2, 26, v2
	s_add_u32 s3, s34, 0x1de00000
	v_add_u32_e32 v2, v0, v2
	s_addc_u32 s19, s35, 0
	v_lshlrev_b32_e32 v1, 3, v12
	v_ashrrev_i32_e32 v13, 6, v2
	v_and_b32_e32 v2, 0xc0, v2
	s_add_u32 s25, s34, 0x3e00000
	v_and_b32_e32 v1, -16, v1
	v_sub_u32_e32 v0, v0, v2
	s_addc_u32 s29, s35, 0
	v_add_u32_e32 v1, v13, v1
	v_ashrrev_i16_sdwa v0, v3, sext(v0) dst_sel:DWORD dst_unused:UNUSED_PAD src0_sel:DWORD src1_sel:BYTE_0
	v_and_b32_e32 v3, 3, v13
	s_ashr_i32 s40, s46, 6
	s_ashr_i32 s15, s14, 31
	s_ashr_i32 s44, s46, 8
	v_and_or_b32 v3, v1, s10, v3
	s_lshl_b32 s70, s40, 10
	s_lshl_b64 s[10:11], s[14:15], 20
	s_add_u32 s60, s3, s10
	s_addc_u32 s61, s19, s11
	s_add_u32 s60, s60, s98
	s_addc_u32 s61, s61, 0
	s_lshl_b64 s[10:11], s[8:9], 20
	s_add_u32 s62, s25, s10
	v_lshlrev_b32_e32 v4, 5, v12
	v_bfe_i32 v14, v0, 0, 16
	v_lshlrev_b32_e32 v0, 1, v1
	v_lshrrev_b32_e32 v2, 2, v1
	s_addc_u32 s63, s29, s11
	s_add_u32 s62, s62, s98
	s_addc_u32 s63, s63, 0
	s_add_i32 s71, s70, 0
	v_and_b32_e32 v4, 32, v4
	v_and_b32_e32 v0, 24, v0
	v_and_b32_e32 v2, 4, v2
	s_add_i32 m0, s71, 0x10000
	v_or3_b32 v0, v3, v2, v0
	v_add_lshl_u32 v2, v4, v14, 1
	global_load_lds_dwordx4 v130, s[62:63]
	s_add_i32 m0, s71, 0x12000
	v_lshl_add_u32 v134, v0, 12, v2
	s_add_u32 s10, s62, 0x80000
	global_load_lds_dwordx4 v134, s[62:63]
	s_addc_u32 s11, s63, 0
	s_add_i32 m0, s71, 0x14000
	s_add_i32 s72, s71, 0x2000
	global_load_lds_dwordx4 v130, s[10:11]
	s_add_i32 m0, s71, 0x16000
	v_lshl_add_u32 v132, v1, 12, v2
	global_load_lds_dwordx4 v134, s[10:11]
	s_mov_b32 m0, s71
	s_add_u32 s10, s60, 0x80000
	global_load_lds_dwordx4 v128, s[60:61]
	s_mov_b32 m0, s72
	s_addc_u32 s11, s61, 0
	s_add_i32 s73, s71, 0x4000
	global_load_lds_dwordx4 v132, s[60:61]
	s_mov_b32 m0, s73
	s_add_i32 s74, s71, 0x6000
	global_load_lds_dwordx4 v128, s[10:11]
	s_mov_b32 m0, s74
	v_mov_b32_e32 v131, 0
	global_load_lds_dwordx4 v132, s[10:11]
	s_load_dwordx2 s[4:5], s[4:5], 0x0
	s_nop 0
	s_load_dwordx2 s[6:7], s[6:7], 0x0
	v_mov_b32_e32 v135, v131
	v_mov_b32_e32 v129, v131
	v_mov_b32_e32 v133, v131
	s_cmp_eq_u32 s44, 1
	s_mov_b32 s28, s96
	s_mov_b32 s51, s99
	s_mov_b32 s9, 0
	v_lshl_add_u64 v[6:7], s[62:63], 0, v[130:131]
	v_lshl_add_u64 v[4:5], s[62:63], 0, v[134:135]
	v_lshl_add_u64 v[0:1], s[60:61], 0, v[128:129]
	s_cselect_b64 s[10:11], -1, 0
	s_cmp_lg_u32 s44, 1
	v_lshl_add_u64 v[2:3], s[60:61], 0, v[132:133]
	s_cbranch_scc1 .LBB0_550
	s_barrier
.LBB0_550:
	s_sub_i32 s58, s14, s101
	s_lshl_b32 s58, s58, 8
	s_lshl_b32 s50, s8, 8
	s_add_u32 s75, s34, 0x20200000
	s_addc_u32 s76, s35, 0
	s_add_u32 s79, s34, 0x19600000
	s_addc_u32 s82, s35, 0
	s_lshl_b32 s12, s40, 5
	s_mov_b64 s[14:15], 0x80
	s_and_b32 s84, s12, 0x60
	s_add_i32 m0, s71, 0x18000
	v_lshl_add_u64 v[6:7], v[6:7], 0, s[14:15]
	s_lshl_b32 s83, s44, 6
	s_lshl_b32 s8, s44, 13
	s_lshl_b32 s12, s84, 7
	s_waitcnt vmcnt(2)
	s_barrier
	global_load_lds_dwordx4 v[6:7], off
	v_lshl_add_u64 v[4:5], v[4:5], 0, s[14:15]
	s_add_i32 m0, s71, 0x1a000
	s_add_i32 s85, s71, 0x8000
	s_add_i32 s86, s71, 0xa000
	global_load_lds_dwordx4 v[4:5], off
	v_lshl_add_u64 v[0:1], v[0:1], 0, s[14:15]
	s_mov_b32 m0, s85
	s_add_u32 s40, s62, 0x80080
	global_load_lds_dwordx4 v[0:1], off
	v_lshl_add_u64 v[0:1], v[2:3], 0, s[14:15]
	s_mov_b32 m0, s86
	s_addc_u32 s41, s63, 0
	global_load_lds_dwordx4 v[0:1], off
	s_add_i32 m0, s71, 0x1c000
	v_lshl_add_u64 v[0:1], s[40:41], 0, v[130:131]
	global_load_lds_dwordx4 v[0:1], off
	v_lshl_add_u64 v[0:1], s[40:41], 0, v[134:135]
	s_add_i32 m0, s71, 0x1e000
	v_bfe_u32 v159, v8, 4, 2
	global_load_lds_dwordx4 v[0:1], off
	v_and_b32_e32 v158, 15, v8
	v_lshlrev_b32_e32 v0, 4, v159
	v_lshlrev_b32_e32 v1, 2, v8
	v_lshl_or_b32 v0, v158, 6, v0
	v_and_b32_e32 v1, 32, v1
	s_cmpk_lt_u32 s46, 0x100
	v_bitop3_b32 v2, v0, s8, v1 bitop3:0xde
	s_cselect_b64 s[44:45], -1, 0
	s_lshl_b32 s8, s2, 5
	v_bitop3_b32 v160, v0, s12, v1 bitop3:0xde
	s_and_b32 s8, s8, 0xe0
	s_ashr_i32 s12, s2, 3
	s_add_i32 s8, s8, s12
	s_ashr_i32 s40, s8, 6
	s_ashr_i32 s41, s40, 31
	s_and_b32 s89, s12, 7
	s_bfe_u32 s8, s8, 0x30003
	s_lshl_b64 s[46:47], s[40:41], 20
	s_add_u32 s12, s3, s46
	s_addc_u32 s13, s19, s47
	s_lshl_b32 s41, s89, 9
	s_add_u32 s12, s12, s41
	v_lshlrev_b32_e32 v0, 15, v12
	s_addc_u32 s13, s13, 0
	v_and_b32_e32 v0, 0xffff0000, v0
	s_add_u32 s46, s12, 0x2000000
	v_lshl_add_u32 v0, v13, 12, v0
	v_and_b32_e32 v1, 1, v12
	s_addc_u32 s47, s13, 0
	s_lshl_b32 s12, s8, 20
	v_lshl_or_b32 v0, v1, 6, v0
	s_add_u32 s12, s25, s12
	v_lshl_add_u32 v136, v14, 1, v0
	v_lshlrev_b32_e32 v0, 15, v9
	s_addc_u32 s13, s29, 0
	v_and_b32_e32 v0, 0xffff0000, v0
	s_waitcnt vmcnt(6)
	s_add_u32 s48, s12, s41
	v_lshl_add_u32 v0, v10, 12, v0
	v_and_b32_e32 v1, 1, v9
	s_addc_u32 s49, s13, 0
	v_lshl_or_b32 v0, v1, 6, v0
	s_add_i32 s90, 0, 0x10000
	s_add_i32 s91, 0, 0x14000
	s_lshl_b32 s40, s40, 8
	s_lshl_b32 s80, s8, 8
	s_add_i32 s89, s89, 1
	v_mov_b32_e32 v137, v131
	v_lshl_add_u32 v138, v11, 1, v0
	v_mov_b32_e32 v139, v131
	v_add_u32_e32 v161, s90, v160
	v_add_u32_e32 v162, s91, v160
	v_add_u32_e32 v163, 0, v2
	s_lshl_b32 s92, s84, 1
	s_mov_b32 s8, s100
	s_mov_b32 s93, 0
	s_mov_b32 s98, 4
	s_bitcmp1_b32 s2, 3
	s_cbranch_scc0 .Lsw4_b
	s_andn2_b64 vcc, exec, s[42:43]
	s_cbranch_vccnz .Lsw4_b
	s_lshl_b32 s12, s2, 5
	s_and_b32 s12, s12, 0xe0
	s_lshr_b32 s13, s2, 3
	s_add_i32 s12, s12, s13
	s_lshr_b32 s40, s12, 3
	s_and_b32 s80, s12, 7
	s_lshl_b32 s13, s40, 20
	s_add_u32 s46, s3, s13
	s_addc_u32 s47, s19, 0
	s_lshl_b32 s13, s80, 20
	s_add_u32 s48, s25, s13
	s_addc_u32 s49, s29, 0
	s_lshl_b32 s40, s40, 8
	s_lshl_b32 s80, s80, 8
	s_mov_b32 s89, 0
	s_mov_b32 s98, 32
.Lsw4_b:
	s_barrier
	s_branch .LBB0_553

.LBB0_572:
	s_mov_b32 s95, s98
	s_mov_b64 s[52:53], -1
	s_mov_b64 s[54:55], s[46:47]
	s_mov_b64 s[56:57], s[48:49]
	s_mov_b32 s87, s40
	s_mov_b32 s88, s80
	s_mov_b32 s97, s89
	s_andn2_b64 vcc, exec, s[68:69]
	s_add_i32 s93, s93, 1
	s_cbranch_vccz .LBB0_556
	s_branch .LBB0_559
